# first K-loop iteration peeled with C=0 MFMAs in all three GEMM phases (no accumulator clears), plus attention bias direct-load and P4 load hoisting
# speedup vs baseline: 1.0214x; 1.0060x over previous
; #define PG8_STAGE(bufoff, gbase, voff) do { _Pragma("unroll") for (int _i = 0; _i < 2; ++_i) \
;         __builtin_amdgcn_global_load_lds((const unsigned*)((const char*)(gbase) + (voff)[_i]), (PG8_LAS unsigned*)(lds + (bufoff) + ldsw + _i * 8192), 16, 0, 0); } while (0)
; #define PG8_LDA(dst, b, h) do { _Pragma("unroll") for (int m = 0; m < 4; ++m) _Pragma("unroll") for (int k = 0; k < 2; ++k) dst[m][k] = *(const PG8_LAS bf16x8*)(lds + PG8_SA(b, h) + aoff + m * 2048 + k * 1024); } while (0)
; #define PG8_LDB(dst, b, h) do { _Pragma("unroll") for (int n = 0; n < 2; ++n) _Pragma("unroll") for (int k = 0; k < 2; ++k) dst[n][k] = *(const PG8_LAS bf16x8*)(lds + PG8_SB(b, h) + boff + n * 2048 + k * 1024); } while (0)
; #define PG8_MMA(ai, bj, At, Bt) do { __builtin_amdgcn_s_setprio(1); _Pragma("unroll") for (int m = 0; m < 4; ++m) _Pragma("unroll") for (int n = 0; n < 2; ++n) _Pragma("unroll") for (int k = 0; k < 2; ++k) \
;         acc[ai][bj][m][n] = __builtin_amdgcn_mfma_f32_16x16x32_bf16(Bt[n][k], At[m][k], acc[ai][bj][m][n], 0, 0, 0); __builtin_amdgcn_s_setprio(0); } while (0)
; #define PG8_WAIT_V(n) asm volatile("s_waitcnt vmcnt(" #n ")" ::: "memory")
; #define PG8_WAIT_L(n) asm volatile("s_waitcnt lgkmcnt(" #n ")" ::: "memory")
; #define PG8_BAR __builtin_amdgcn_s_barrier()
; #define PG8_SCHED __builtin_amdgcn_sched_barrier(0)
; template <class Epi, class Sched, bool ALIGN_EPI = false, bool SP2 = false>
; __device__ __forceinline__ void gemm_phase(PG8_LAS unsigned char* lds, const Gemm g, const Sched& S, const Epi& E) {
;     ...
;             PG8_LDB(B0, 0, 0); PG8_LDB(B1, 0, 1); PG8_SCHED; PG8_LDA(At, 0, 0); PG8_STAGE(PG8_SA(1, 1), a1 + hstep, voffA);
;             PG8_WAIT_V(8); PG8_WAIT_L(0); PG8_BAR; PG8_MMA(0, 0, At, B0); PG8_MMA(0, 1, At, B1); PG8_BAR; PG8_SCHED;
;             PG8_LDA(At, 0, 1); PG8_STAGE(PG8_SB(0, 0), b2, voffB); PG8_STAGE(PG8_SB(0, 1), b2 + hstep, voffB); PG8_STAGE(PG8_SA(0, 0), a2, voffA);
;             PG8_WAIT_V(8); PG8_WAIT_L(0); PG8_BAR; PG8_MMA(1, 0, At, B0); PG8_MMA(1, 1, At, B1); PG8_BAR; PG8_SCHED;
;     ...
; #pragma unroll
;         for (int a = 0; a < 2; ++a)
; #pragma unroll
;             for (int b = 0; b < 2; ++b)
; #pragma unroll
;                 for (int m = 0; m < 4; ++m)
; #pragma unroll
;                     for (int n = 0; n < 2; ++n) acc[a][b][m][n] = (f32x4){0.f, 0.f, 0.f, 0.f};
.LBB0_506:
	s_ashr_i32 s23, s22, 31
	s_lshl_b64 s[26:27], s[22:23], 19
	s_add_u32 s26, s43, s26
	s_addc_u32 s27, s44, s27
	s_and_b64 s[28:29], s[4:5], exec
	s_cselect_b32 s23, s27, s31
	s_cselect_b32 s56, s26, s30
	s_ashr_i32 s21, s20, 31
	s_lshl_b64 s[28:29], s[20:21], 19
	s_add_u32 s28, s41, s28
	s_addc_u32 s29, s42, s29
	s_and_b64 s[38:39], s[4:5], exec
	s_cselect_b32 s21, s29, s37
	s_cselect_b32 s57, s28, s36
	s_lshl_b32 s34, s34, 18
	s_lshl_b32 s35, s35, 8
	s_add_i32 s34, s34, s35
	s_add_u32 s58, s36, 0x100
	v_add_u32_e32 v168, s34, v174
	v_lshl_add_u64 v[170:171], s[30:31], 0, v[160:161]
	v_lshl_add_u64 v[172:173], s[30:31], 0, v[162:163]
	s_addc_u32 s59, s37, 0
	s_mov_b32 s60, -2
	s_mov_b64 s[34:35], 0
	v_add_u32_e32 v2, s54, v1
	ds_read_b128 v[134:137], v2
	ds_read_b128 v[138:141], v2 offset:1024
	ds_read_b128 v[142:145], v2 offset:2048
	ds_read_b128 v[146:149], v2 offset:3072
	v_add_u32_e32 v2, s55, v1
	s_add_u32 s36, s30, s34
	ds_read_b128 v[176:179], v2
	ds_read_b128 v[180:183], v2 offset:1024
	ds_read_b128 v[184:187], v2 offset:2048
	ds_read_b128 v[188:191], v2 offset:3072
	s_addc_u32 s37, s31, s35
	s_add_u32 s36, s36, 0x100
	s_addc_u32 s37, s37, 0
	s_add_u32 s61, s58, s34
	s_addc_u32 s62, s59, s35
	s_cmpk_eq_i32 s34, 0x700
	s_cselect_b32 s39, s23, s37
	s_cselect_b32 s38, s56, s36
	s_cselect_b32 s37, s21, s62
	s_cselect_b32 s36, s57, s61
	v_lshl_add_u64 v[4:5], v[170:171], 0, s[34:35]
	s_add_i32 m0, s46, 0xc000
	ds_read_b128 v[192:195], v175
	ds_read_b128 v[196:199], v175 offset:1024
	ds_read_b128 v[200:203], v175 offset:2048
	ds_read_b128 v[204:207], v175 offset:3072
	ds_read_b128 v[208:211], v175 offset:4096
	ds_read_b128 v[212:215], v175 offset:5120
	ds_read_b128 v[216:219], v175 offset:6144
	ds_read_b128 v[220:223], v175 offset:7168
	global_load_lds_dwordx4 v[4:5], off
	v_lshl_add_u64 v[4:5], v[172:173], 0, s[34:35]
	s_add_i32 m0, s46, 0xe000
	s_nop 0
	global_load_lds_dwordx4 v[4:5], off
	s_waitcnt vmcnt(8)
	s_waitcnt lgkmcnt(0)
	s_barrier
	s_setprio 1
	s_waitcnt lgkmcnt(0)
	v_mfma_f32_16x16x32_bf16 v[130:133], v[134:137], v[192:195], 0
	v_mfma_f32_16x16x32_bf16 v[126:129], v[142:145], v[192:195], 0
	v_mfma_f32_16x16x32_bf16 v[114:117], v[134:137], v[200:203], 0
	v_mfma_f32_16x16x32_bf16 v[110:113], v[142:145], v[200:203], 0
	v_mfma_f32_16x16x32_bf16 v[98:101], v[134:137], v[208:211], 0
	v_mfma_f32_16x16x32_bf16 v[94:97], v[142:145], v[208:211], 0
	v_mfma_f32_16x16x32_bf16 v[82:85], v[134:137], v[216:219], 0
	v_mfma_f32_16x16x32_bf16 v[78:81], v[142:145], v[216:219], 0
	v_mfma_f32_16x16x32_bf16 v[130:133], v[138:141], v[196:199], v[130:133]
	v_mfma_f32_16x16x32_bf16 v[126:129], v[146:149], v[196:199], v[126:129]
	v_mfma_f32_16x16x32_bf16 v[114:117], v[138:141], v[204:207], v[114:117]
	v_mfma_f32_16x16x32_bf16 v[110:113], v[146:149], v[204:207], v[110:113]
	v_mfma_f32_16x16x32_bf16 v[98:101], v[138:141], v[212:215], v[98:101]
	v_mfma_f32_16x16x32_bf16 v[94:97], v[146:149], v[212:215], v[94:97]
	v_mfma_f32_16x16x32_bf16 v[82:85], v[138:141], v[220:223], v[82:85]
	v_mfma_f32_16x16x32_bf16 v[78:81], v[146:149], v[220:223], v[78:81]
	s_setprio 0
	s_setprio 1
	v_mfma_f32_16x16x32_bf16 v[122:125], v[176:179], v[192:195], 0
	v_mfma_f32_16x16x32_bf16 v[118:121], v[184:187], v[192:195], 0
	v_mfma_f32_16x16x32_bf16 v[106:109], v[176:179], v[200:203], 0
	v_mfma_f32_16x16x32_bf16 v[102:105], v[184:187], v[200:203], 0
	v_mfma_f32_16x16x32_bf16 v[90:93], v[176:179], v[208:211], 0
	v_mfma_f32_16x16x32_bf16 v[86:89], v[184:187], v[208:211], 0
	v_mfma_f32_16x16x32_bf16 v[74:77], v[176:179], v[216:219], 0
	v_mfma_f32_16x16x32_bf16 v[70:73], v[184:187], v[216:219], 0
	v_mfma_f32_16x16x32_bf16 v[122:125], v[180:183], v[196:199], v[122:125]
	v_mfma_f32_16x16x32_bf16 v[118:121], v[188:191], v[196:199], v[118:121]
	v_mfma_f32_16x16x32_bf16 v[106:109], v[180:183], v[204:207], v[106:109]
	v_mfma_f32_16x16x32_bf16 v[102:105], v[188:191], v[204:207], v[102:105]
	v_mfma_f32_16x16x32_bf16 v[90:93], v[180:183], v[212:215], v[90:93]
	v_mfma_f32_16x16x32_bf16 v[86:89], v[188:191], v[212:215], v[86:89]
	v_mfma_f32_16x16x32_bf16 v[74:77], v[180:183], v[220:223], v[74:77]
	v_mfma_f32_16x16x32_bf16 v[70:73], v[188:191], v[220:223], v[70:73]
	s_setprio 0
	s_barrier
	s_add_i32 s61, s54, s45
	v_lshl_add_u64 v[150:151], s[36:37], 0, v[154:155]
	s_mov_b32 m0, s61
	ds_read_b128 v[192:195], v175 offset:16384
	ds_read_b128 v[196:199], v175 offset:17408
	ds_read_b128 v[200:203], v175 offset:18432
	ds_read_b128 v[204:207], v175 offset:19456
	ds_read_b128 v[208:211], v175 offset:20480
	ds_read_b128 v[212:215], v175 offset:21504
	ds_read_b128 v[216:219], v175 offset:22528
	ds_read_b128 v[220:223], v175 offset:23552
	global_load_lds_dwordx4 v[150:151], off
	s_add_i32 m0, s61, 0x2000
	s_add_u32 s62, s36, 0x40000
	v_lshl_add_u64 v[224:225], s[36:37], 0, v[158:159]
	s_addc_u32 s63, s37, 0
	s_add_i32 s61, s55, s45
	global_load_lds_dwordx4 v[224:225], off
	v_lshl_add_u64 v[4:5], s[62:63], 0, v[154:155]
	s_mov_b32 m0, s61
	v_lshl_add_u64 v[226:227], s[38:39], 0, v[152:153]
	global_load_lds_dwordx4 v[4:5], off
	v_lshl_add_u64 v[4:5], s[62:63], 0, v[158:159]
	s_add_i32 m0, s61, 0x2000
	v_lshl_add_u64 v[228:229], s[38:39], 0, v[156:157]
	global_load_lds_dwordx4 v[4:5], off
	s_mov_b32 m0, s46
	s_nop 0
	global_load_lds_dwordx4 v[226:227], off
	s_mov_b32 m0, s47
	s_nop 0
	global_load_lds_dwordx4 v[228:229], off
	s_waitcnt vmcnt(8)
	s_waitcnt lgkmcnt(0)
	s_barrier
; #define PG8_STAGE(bufoff, gbase, voff) do { _Pragma("unroll") for (int _i = 0; _i < 2; ++_i) \
;         __builtin_amdgcn_global_load_lds((const unsigned*)((const char*)(gbase) + (voff)[_i]), (PG8_LAS unsigned*)(lds + (bufoff) + ldsw + _i * 8192), 16, 0, 0); } while (0)
; #define PG8_LDA(dst, b, h) do { _Pragma("unroll") for (int m = 0; m < 4; ++m) _Pragma("unroll") for (int k = 0; k < 2; ++k) dst[m][k] = *(const PG8_LAS bf16x8*)(lds + PG8_SA(b, h) + aoff + m * 2048 + k * 1024); } while (0)
; #define PG8_LDB(dst, b, h) do { _Pragma("unroll") for (int n = 0; n < 2; ++n) _Pragma("unroll") for (int k = 0; k < 2; ++k) dst[n][k] = *(const PG8_LAS bf16x8*)(lds + PG8_SB(b, h) + boff + n * 2048 + k * 1024); } while (0)
; #define PG8_MMA(ai, bj, At, Bt) do { __builtin_amdgcn_s_setprio(1); _Pragma("unroll") for (int m = 0; m < 4; ++m) _Pragma("unroll") for (int n = 0; n < 2; ++n) _Pragma("unroll") for (int k = 0; k < 2; ++k) \
;         acc[ai][bj][m][n] = __builtin_amdgcn_mfma_f32_16x16x32_bf16(Bt[n][k], At[m][k], acc[ai][bj][m][n], 0, 0, 0); __builtin_amdgcn_s_setprio(0); } while (0)
; #define PG8_WAIT_V(n) asm volatile("s_waitcnt vmcnt(" #n ")" ::: "memory")
; #define PG8_WAIT_L(n) asm volatile("s_waitcnt lgkmcnt(" #n ")" ::: "memory")
; #define PG8_BAR __builtin_amdgcn_s_barrier()
; #define PG8_SCHED __builtin_amdgcn_sched_barrier(0)
; template <class Epi, class Sched, bool ALIGN_EPI = false, bool SP2 = false>
; __device__ __forceinline__ void gemm_phase(PG8_LAS unsigned char* lds, const Gemm g, const Sched& S, const Epi& E) {
;     ...
;             PG8_WAIT_V(8); PG8_WAIT_L(0); PG8_BAR; PG8_MMA(1, 0, At, B0); PG8_MMA(1, 1, At, B1); PG8_BAR; PG8_SCHED;
;             PG8_LDB(B0, 1, 0); PG8_LDB(B1, 1, 1); PG8_SCHED; PG8_LDA(At, 1, 0); PG8_STAGE(PG8_SA(0, 1), a2 + hstep, voffA);
;             PG8_WAIT_V(8); PG8_WAIT_L(0); PG8_BAR; PG8_MMA(0, 0, At, B0); PG8_MMA(0, 1, At, B1); PG8_BAR; PG8_SCHED;
	s_setprio 1
	s_waitcnt lgkmcnt(0)
	v_mfma_f32_16x16x32_bf16 v[66:69], v[134:137], v[192:195], 0
	v_mfma_f32_16x16x32_bf16 v[62:65], v[142:145], v[192:195], 0
	v_mfma_f32_16x16x32_bf16 v[50:53], v[134:137], v[200:203], 0
	v_mfma_f32_16x16x32_bf16 v[46:49], v[142:145], v[200:203], 0
	v_mfma_f32_16x16x32_bf16 v[34:37], v[134:137], v[208:211], 0
	v_mfma_f32_16x16x32_bf16 v[30:33], v[142:145], v[208:211], 0
	v_mfma_f32_16x16x32_bf16 v[18:21], v[134:137], v[216:219], 0
	v_mfma_f32_16x16x32_bf16 v[14:17], v[142:145], v[216:219], 0
	v_mfma_f32_16x16x32_bf16 v[66:69], v[138:141], v[196:199], v[66:69]
	v_mfma_f32_16x16x32_bf16 v[62:65], v[146:149], v[196:199], v[62:65]
	v_mfma_f32_16x16x32_bf16 v[50:53], v[138:141], v[204:207], v[50:53]
	v_mfma_f32_16x16x32_bf16 v[46:49], v[146:149], v[204:207], v[46:49]
	v_mfma_f32_16x16x32_bf16 v[34:37], v[138:141], v[212:215], v[34:37]
	v_mfma_f32_16x16x32_bf16 v[30:33], v[146:149], v[212:215], v[30:33]
	v_mfma_f32_16x16x32_bf16 v[18:21], v[138:141], v[220:223], v[18:21]
	v_mfma_f32_16x16x32_bf16 v[14:17], v[146:149], v[220:223], v[14:17]
	s_setprio 0
	s_setprio 1
	v_mfma_f32_16x16x32_bf16 v[58:61], v[176:179], v[192:195], 0
	v_mfma_f32_16x16x32_bf16 v[54:57], v[184:187], v[192:195], 0
	v_mfma_f32_16x16x32_bf16 v[42:45], v[176:179], v[200:203], 0
	v_mfma_f32_16x16x32_bf16 v[38:41], v[184:187], v[200:203], 0
	v_mfma_f32_16x16x32_bf16 v[26:29], v[176:179], v[208:211], 0
	v_mfma_f32_16x16x32_bf16 v[22:25], v[184:187], v[208:211], 0
	v_mfma_f32_16x16x32_bf16 v[10:13], v[176:179], v[216:219], 0
	v_mfma_f32_16x16x32_bf16 v[4:7], v[184:187], v[216:219], 0
	v_mfma_f32_16x16x32_bf16 v[58:61], v[180:183], v[196:199], v[58:61]
	v_mfma_f32_16x16x32_bf16 v[54:57], v[188:191], v[196:199], v[54:57]
	v_mfma_f32_16x16x32_bf16 v[42:45], v[180:183], v[204:207], v[42:45]
	v_mfma_f32_16x16x32_bf16 v[38:41], v[188:191], v[204:207], v[38:41]
	v_mfma_f32_16x16x32_bf16 v[26:29], v[180:183], v[212:215], v[26:29]
	v_mfma_f32_16x16x32_bf16 v[22:25], v[188:191], v[212:215], v[22:25]
	v_mfma_f32_16x16x32_bf16 v[10:13], v[180:183], v[220:223], v[10:13]
	v_mfma_f32_16x16x32_bf16 v[4:7], v[188:191], v[220:223], v[4:7]
	s_setprio 0
	s_barrier
	s_add_i32 s61, 0, 0x18000
	v_add_u32_e32 v2, s61, v1
	s_add_i32 s62, 0, 0x1c000
	ds_read_b128 v[134:137], v2
	ds_read_b128 v[138:141], v2 offset:1024
	ds_read_b128 v[142:145], v2 offset:2048
	ds_read_b128 v[146:149], v2 offset:3072
	v_add_u32_e32 v2, s62, v1
	ds_read_b128 v[176:179], v2
	ds_read_b128 v[180:183], v2 offset:1024
	ds_read_b128 v[184:187], v2 offset:2048
	ds_read_b128 v[188:191], v2 offset:3072
	s_add_u32 s38, s38, 0x40000
	s_addc_u32 s39, s39, 0
	s_mov_b32 m0, s48
	v_lshl_add_u64 v[8:9], s[38:39], 0, v[152:153]
	ds_read_b128 v[192:195], v175 offset:32768
	ds_read_b128 v[196:199], v175 offset:33792
	ds_read_b128 v[200:203], v175 offset:34816
	ds_read_b128 v[204:207], v175 offset:35840
	ds_read_b128 v[208:211], v175 offset:36864
	ds_read_b128 v[212:215], v175 offset:37888
	ds_read_b128 v[216:219], v175 offset:38912
	ds_read_b128 v[220:223], v175 offset:39936
	global_load_lds_dwordx4 v[8:9], off
	v_lshl_add_u64 v[8:9], s[38:39], 0, v[156:157]
	s_mov_b32 m0, s49
	s_nop 0
	global_load_lds_dwordx4 v[8:9], off
	s_waitcnt vmcnt(8)
	s_waitcnt lgkmcnt(0)
	s_barrier
	s_setprio 1
	s_waitcnt lgkmcnt(0)
	v_mfma_f32_16x16x32_bf16 v[130:133], v[134:137], v[192:195], v[130:133]
	v_mfma_f32_16x16x32_bf16 v[126:129], v[142:145], v[192:195], v[126:129]
	v_mfma_f32_16x16x32_bf16 v[114:117], v[134:137], v[200:203], v[114:117]
	v_mfma_f32_16x16x32_bf16 v[110:113], v[142:145], v[200:203], v[110:113]
	v_mfma_f32_16x16x32_bf16 v[98:101], v[134:137], v[208:211], v[98:101]
	v_mfma_f32_16x16x32_bf16 v[94:97], v[142:145], v[208:211], v[94:97]
	v_mfma_f32_16x16x32_bf16 v[82:85], v[134:137], v[216:219], v[82:85]
	v_mfma_f32_16x16x32_bf16 v[78:81], v[142:145], v[216:219], v[78:81]
	v_mfma_f32_16x16x32_bf16 v[130:133], v[138:141], v[196:199], v[130:133]
	v_mfma_f32_16x16x32_bf16 v[126:129], v[146:149], v[196:199], v[126:129]
	v_mfma_f32_16x16x32_bf16 v[114:117], v[138:141], v[204:207], v[114:117]
	v_mfma_f32_16x16x32_bf16 v[110:113], v[146:149], v[204:207], v[110:113]
	v_mfma_f32_16x16x32_bf16 v[98:101], v[138:141], v[212:215], v[98:101]
	v_mfma_f32_16x16x32_bf16 v[94:97], v[146:149], v[212:215], v[94:97]
	v_mfma_f32_16x16x32_bf16 v[82:85], v[138:141], v[220:223], v[82:85]
	v_mfma_f32_16x16x32_bf16 v[78:81], v[146:149], v[220:223], v[78:81]
	s_setprio 0
	s_setprio 1
	v_mfma_f32_16x16x32_bf16 v[122:125], v[176:179], v[192:195], v[122:125]
	v_mfma_f32_16x16x32_bf16 v[118:121], v[184:187], v[192:195], v[118:121]
	v_mfma_f32_16x16x32_bf16 v[106:109], v[176:179], v[200:203], v[106:109]
	v_mfma_f32_16x16x32_bf16 v[102:105], v[184:187], v[200:203], v[102:105]
	v_mfma_f32_16x16x32_bf16 v[90:93], v[176:179], v[208:211], v[90:93]
	v_mfma_f32_16x16x32_bf16 v[86:89], v[184:187], v[208:211], v[86:89]
	v_mfma_f32_16x16x32_bf16 v[74:77], v[176:179], v[216:219], v[74:77]
	v_mfma_f32_16x16x32_bf16 v[70:73], v[184:187], v[216:219], v[70:73]
	v_mfma_f32_16x16x32_bf16 v[122:125], v[180:183], v[196:199], v[122:125]
	v_mfma_f32_16x16x32_bf16 v[118:121], v[188:191], v[196:199], v[118:121]
	v_mfma_f32_16x16x32_bf16 v[106:109], v[180:183], v[204:207], v[106:109]
	v_mfma_f32_16x16x32_bf16 v[102:105], v[188:191], v[204:207], v[102:105]
	v_mfma_f32_16x16x32_bf16 v[90:93], v[180:183], v[212:215], v[90:93]
	v_mfma_f32_16x16x32_bf16 v[86:89], v[188:191], v[212:215], v[86:89]
	v_mfma_f32_16x16x32_bf16 v[74:77], v[180:183], v[220:223], v[74:77]
	v_mfma_f32_16x16x32_bf16 v[70:73], v[188:191], v[220:223], v[70:73]
	s_setprio 0
	s_barrier
; #define PG8_STAGE(bufoff, gbase, voff) do { _Pragma("unroll") for (int _i = 0; _i < 2; ++_i) \
;         __builtin_amdgcn_global_load_lds((const unsigned*)((const char*)(gbase) + (voff)[_i]), (PG8_LAS unsigned*)(lds + (bufoff) + ldsw + _i * 8192), 16, 0, 0); } while (0)
; #define PG8_LDA(dst, b, h) do { _Pragma("unroll") for (int m = 0; m < 4; ++m) _Pragma("unroll") for (int k = 0; k < 2; ++k) dst[m][k] = *(const PG8_LAS bf16x8*)(lds + PG8_SA(b, h) + aoff + m * 2048 + k * 1024); } while (0)
; #define PG8_MMA(ai, bj, At, Bt) do { __builtin_amdgcn_s_setprio(1); _Pragma("unroll") for (int m = 0; m < 4; ++m) _Pragma("unroll") for (int n = 0; n < 2; ++n) _Pragma("unroll") for (int k = 0; k < 2; ++k) \
;         acc[ai][bj][m][n] = __builtin_amdgcn_mfma_f32_16x16x32_bf16(Bt[n][k], At[m][k], acc[ai][bj][m][n], 0, 0, 0); __builtin_amdgcn_s_setprio(0); } while (0)
; #define PG8_WAIT_V(n) asm volatile("s_waitcnt vmcnt(" #n ")" ::: "memory")
; #define PG8_WAIT_L(n) asm volatile("s_waitcnt lgkmcnt(" #n ")" ::: "memory")
; #define PG8_BAR __builtin_amdgcn_s_barrier()
; #define PG8_SCHED __builtin_amdgcn_sched_barrier(0)
; template <class Epi, class Sched, bool ALIGN_EPI = false, bool SP2 = false>
; __device__ __forceinline__ void gemm_phase(PG8_LAS unsigned char* lds, const Gemm g, const Sched& S, const Epi& E) {
;     ...
;         for (int t = 0; t < nt; t += 2) {
;             if constexpr (Epi::MID) { if (t == nt / 2) E.mid(acc, cur, wr, wc, fr, fq); }
;     ...
;             PG8_LDA(At, 1, 1); PG8_STAGE(PG8_SB(1, 0), b3, voffB); PG8_STAGE(PG8_SB(1, 1), b3 + hstep, voffB); PG8_STAGE(PG8_SA(1, 0), a3, voffA);
;             PG8_WAIT_V(8); PG8_WAIT_L(0); PG8_BAR; PG8_MMA(1, 0, At, B0); PG8_MMA(1, 1, At, B1); PG8_BAR; PG8_SCHED;
	s_add_i32 s38, s61, s45
	v_lshl_add_u64 v[8:9], v[150:151], 0, s[12:13]
	s_mov_b32 m0, s38
	ds_read_b128 v[192:195], v175 offset:49152
	ds_read_b128 v[196:199], v175 offset:50176
	ds_read_b128 v[200:203], v175 offset:51200
	ds_read_b128 v[204:207], v175 offset:52224
	ds_read_b128 v[208:211], v175 offset:53248
	ds_read_b128 v[212:215], v175 offset:54272
	ds_read_b128 v[216:219], v175 offset:55296
	ds_read_b128 v[220:223], v175 offset:56320
	global_load_lds_dwordx4 v[8:9], off
	s_add_i32 m0, s38, 0x2000
	s_add_u32 s36, s36, 0x40080
	v_lshl_add_u64 v[8:9], v[224:225], 0, s[12:13]
	s_addc_u32 s37, s37, 0
	s_add_i32 s38, s62, s45
	global_load_lds_dwordx4 v[8:9], off
	v_lshl_add_u64 v[8:9], s[36:37], 0, v[154:155]
	s_mov_b32 m0, s38
	s_nop 0
	global_load_lds_dwordx4 v[8:9], off
	v_lshl_add_u64 v[8:9], s[36:37], 0, v[158:159]
	s_add_i32 m0, s38, 0x2000
	s_nop 0
	global_load_lds_dwordx4 v[8:9], off
	v_lshl_add_u64 v[8:9], v[226:227], 0, s[12:13]
	s_mov_b32 m0, s51
	s_nop 0
	global_load_lds_dwordx4 v[8:9], off
	v_lshl_add_u64 v[8:9], v[228:229], 0, s[12:13]
	s_mov_b32 m0, s52
	s_nop 0
	global_load_lds_dwordx4 v[8:9], off
	s_waitcnt vmcnt(8)
	s_waitcnt lgkmcnt(0)
	s_barrier
	s_setprio 1
	s_waitcnt lgkmcnt(0)
	v_mfma_f32_16x16x32_bf16 v[66:69], v[134:137], v[192:195], v[66:69]
	v_mfma_f32_16x16x32_bf16 v[62:65], v[142:145], v[192:195], v[62:65]
	v_mfma_f32_16x16x32_bf16 v[50:53], v[134:137], v[200:203], v[50:53]
	v_mfma_f32_16x16x32_bf16 v[46:49], v[142:145], v[200:203], v[46:49]
	v_mfma_f32_16x16x32_bf16 v[34:37], v[134:137], v[208:211], v[34:37]
	v_mfma_f32_16x16x32_bf16 v[30:33], v[142:145], v[208:211], v[30:33]
	v_mfma_f32_16x16x32_bf16 v[18:21], v[134:137], v[216:219], v[18:21]
	v_mfma_f32_16x16x32_bf16 v[14:17], v[142:145], v[216:219], v[14:17]
	v_mfma_f32_16x16x32_bf16 v[66:69], v[138:141], v[196:199], v[66:69]
	v_mfma_f32_16x16x32_bf16 v[62:65], v[146:149], v[196:199], v[62:65]
	v_mfma_f32_16x16x32_bf16 v[50:53], v[138:141], v[204:207], v[50:53]
	v_mfma_f32_16x16x32_bf16 v[46:49], v[146:149], v[204:207], v[46:49]
	v_mfma_f32_16x16x32_bf16 v[34:37], v[138:141], v[212:215], v[34:37]
	v_mfma_f32_16x16x32_bf16 v[30:33], v[146:149], v[212:215], v[30:33]
	v_mfma_f32_16x16x32_bf16 v[18:21], v[138:141], v[220:223], v[18:21]
	v_mfma_f32_16x16x32_bf16 v[14:17], v[146:149], v[220:223], v[14:17]
	s_setprio 0
	s_setprio 1
	v_mfma_f32_16x16x32_bf16 v[58:61], v[176:179], v[192:195], v[58:61]
	v_mfma_f32_16x16x32_bf16 v[54:57], v[184:187], v[192:195], v[54:57]
	v_mfma_f32_16x16x32_bf16 v[42:45], v[176:179], v[200:203], v[42:45]
	v_mfma_f32_16x16x32_bf16 v[38:41], v[184:187], v[200:203], v[38:41]
	v_mfma_f32_16x16x32_bf16 v[26:29], v[176:179], v[208:211], v[26:29]
	v_mfma_f32_16x16x32_bf16 v[22:25], v[184:187], v[208:211], v[22:25]
	v_mfma_f32_16x16x32_bf16 v[8:11], v[176:179], v[216:219], v[10:13]
	v_mfma_f32_16x16x32_bf16 v[4:7], v[184:187], v[216:219], v[4:7]
	v_mfma_f32_16x16x32_bf16 v[58:61], v[180:183], v[196:199], v[58:61]
	v_mfma_f32_16x16x32_bf16 v[54:57], v[188:191], v[196:199], v[54:57]
	v_mfma_f32_16x16x32_bf16 v[42:45], v[180:183], v[204:207], v[42:45]
	v_mfma_f32_16x16x32_bf16 v[38:41], v[188:191], v[204:207], v[38:41]
	v_mfma_f32_16x16x32_bf16 v[26:29], v[180:183], v[212:215], v[26:29]
	v_mfma_f32_16x16x32_bf16 v[22:25], v[188:191], v[212:215], v[22:25]
	v_mfma_f32_16x16x32_bf16 v[10:13], v[180:183], v[220:223], v[8:11]
	v_mfma_f32_16x16x32_bf16 v[6:9], v[188:191], v[220:223], v[4:7]
	s_setprio 0
	s_barrier
	s_add_i32 s60, s60, 2
	s_add_u32 s34, s34, 0x100
	s_addc_u32 s35, s35, 0
	s_cmp_gt_u32 s60, 13
	s_cbranch_scc1 .LBB0_510
	s_branch .LBB0_508

; #define PG8_STAGE(bufoff, gbase, voff) do { _Pragma("unroll") for (int _i = 0; _i < 2; ++_i) \
;         __builtin_amdgcn_global_load_lds((const unsigned*)((const char*)(gbase) + (voff)[_i]), (PG8_LAS unsigned*)(lds + (bufoff) + ldsw + _i * 8192), 16, 0, 0); } while (0)
; #define PG8_LDA(dst, b, h) do { _Pragma("unroll") for (int m = 0; m < 4; ++m) _Pragma("unroll") for (int k = 0; k < 2; ++k) dst[m][k] = *(const PG8_LAS bf16x8*)(lds + PG8_SA(b, h) + aoff + m * 2048 + k * 1024); } while (0)
; #define PG8_LDB(dst, b, h) do { _Pragma("unroll") for (int n = 0; n < 2; ++n) _Pragma("unroll") for (int k = 0; k < 2; ++k) dst[n][k] = *(const PG8_LAS bf16x8*)(lds + PG8_SB(b, h) + boff + n * 2048 + k * 1024); } while (0)
; #define PG8_MMA(ai, bj, At, Bt) do { __builtin_amdgcn_s_setprio(1); _Pragma("unroll") for (int m = 0; m < 4; ++m) _Pragma("unroll") for (int n = 0; n < 2; ++n) _Pragma("unroll") for (int k = 0; k < 2; ++k) \
;         acc[ai][bj][m][n] = __builtin_amdgcn_mfma_f32_16x16x32_bf16(Bt[n][k], At[m][k], acc[ai][bj][m][n], 0, 0, 0); __builtin_amdgcn_s_setprio(0); } while (0)
; #define PG8_WAIT_V(n) asm volatile("s_waitcnt vmcnt(" #n ")" ::: "memory")
; #define PG8_WAIT_L(n) asm volatile("s_waitcnt lgkmcnt(" #n ")" ::: "memory")
; #define PG8_BAR __builtin_amdgcn_s_barrier()
; #define PG8_SCHED __builtin_amdgcn_sched_barrier(0)
; template <class Epi, class Sched, bool ALIGN_EPI = false, bool SP2 = false>
; __device__ __forceinline__ void gemm_phase(PG8_LAS unsigned char* lds, const Gemm g, const Sched& S, const Epi& E) {
;     ...
;             PG8_LDB(B0, 0, 0); PG8_LDB(B1, 0, 1); PG8_SCHED; PG8_LDA(At, 0, 0); PG8_STAGE(PG8_SA(1, 1), a1 + hstep, voffA);
;             PG8_WAIT_V(8); PG8_WAIT_L(0); PG8_BAR; PG8_MMA(0, 0, At, B0); PG8_MMA(0, 1, At, B1); PG8_BAR; PG8_SCHED;
;             PG8_LDA(At, 0, 1); PG8_STAGE(PG8_SB(0, 0), b2, voffB); PG8_STAGE(PG8_SB(0, 1), b2 + hstep, voffB); PG8_STAGE(PG8_SA(0, 0), a2, voffA);
;             PG8_WAIT_V(8); PG8_WAIT_L(0); PG8_BAR; PG8_MMA(1, 0, At, B0); PG8_MMA(1, 1, At, B1); PG8_BAR; PG8_SCHED;
;     ...
; #pragma unroll
;         for (int a = 0; a < 2; ++a)
; #pragma unroll
;             for (int b = 0; b < 2; ++b)
; #pragma unroll
;                 for (int m = 0; m < 4; ++m)
; #pragma unroll
;                     for (int n = 0; n < 2; ++n) acc[a][b][m][n] = (f32x4){0.f, 0.f, 0.f, 0.f};
.LBB0_584:
	s_ashr_i32 s25, s24, 31
	s_lshl_b64 s[26:27], s[24:25], 19
	s_add_u32 s26, s42, s26
	s_addc_u32 s27, s43, s27
	s_and_b64 s[28:29], s[0:1], exec
	s_cselect_b32 s25, s27, s35
	s_cselect_b32 s31, s26, s34
	s_ashr_i32 s23, s22, 31
	s_lshl_b64 s[28:29], s[22:23], 19
	s_add_u32 s28, s40, s28
	s_addc_u32 s29, s41, s29
	s_and_b64 s[38:39], s[0:1], exec
	s_cselect_b32 s23, s29, s37
	s_cselect_b32 s62, s28, s36
	s_add_u32 s34, s34, 0x40080
	s_addc_u32 s35, s35, 0
	s_add_u32 s63, s36, 0x100
	s_addc_u32 s64, s37, 0
	s_mov_b32 s65, -2
	ds_read_b128 v[128:131], v164
	ds_read_b128 v[132:135], v164 offset:1024
	ds_read_b128 v[136:139], v164 offset:2048
	ds_read_b128 v[140:143], v164 offset:3072
	ds_read_b128 v[158:161], v165
	ds_read_b128 v[168:171], v165 offset:1024
	ds_read_b128 v[172:175], v165 offset:2048
	ds_read_b128 v[176:179], v165 offset:3072
	s_add_u32 s36, s34, 0xfffc0080
	s_addc_u32 s37, s35, -1
	s_cmp_eq_u32 s65, 12
	s_cselect_b32 s39, s25, s37
	s_cselect_b32 s38, s31, s36
	s_cselect_b32 s37, s23, s64
	s_cselect_b32 s36, s62, s63
	v_lshl_add_u64 v[212:213], s[34:35], 0, v[150:151]
	s_add_i32 m0, s45, 0xc000
	ds_read_b128 v[180:183], v166
	ds_read_b128 v[184:187], v166 offset:1024
	ds_read_b128 v[188:191], v166 offset:2048
	ds_read_b128 v[192:195], v166 offset:3072
	ds_read_b128 v[196:199], v166 offset:4096
	ds_read_b128 v[200:203], v166 offset:5120
	ds_read_b128 v[204:207], v166 offset:6144
	ds_read_b128 v[208:211], v166 offset:7168
	global_load_lds_dwordx4 v[212:213], off
	v_lshl_add_u64 v[212:213], s[34:35], 0, v[152:153]
	s_add_i32 m0, s45, 0xe000
	s_nop 0
	global_load_lds_dwordx4 v[212:213], off
	s_waitcnt vmcnt(8)
	s_waitcnt lgkmcnt(0)
	s_barrier
	s_setprio 1
	s_waitcnt lgkmcnt(0)
	v_mfma_f32_16x16x32_bf16 v[124:127], v[128:131], v[180:183], 0
	v_mfma_f32_16x16x32_bf16 v[120:123], v[136:139], v[180:183], 0
	v_mfma_f32_16x16x32_bf16 v[116:119], v[128:131], v[188:191], 0
	v_mfma_f32_16x16x32_bf16 v[112:115], v[136:139], v[188:191], 0
	v_mfma_f32_16x16x32_bf16 v[108:111], v[128:131], v[196:199], 0
	v_mfma_f32_16x16x32_bf16 v[100:103], v[136:139], v[196:199], 0
	v_mfma_f32_16x16x32_bf16 v[92:95], v[128:131], v[204:207], 0
	v_mfma_f32_16x16x32_bf16 v[76:79], v[136:139], v[204:207], 0
	v_mfma_f32_16x16x32_bf16 v[124:127], v[132:135], v[184:187], v[124:127]
	v_mfma_f32_16x16x32_bf16 v[120:123], v[140:143], v[184:187], v[120:123]
	v_mfma_f32_16x16x32_bf16 v[116:119], v[132:135], v[192:195], v[116:119]
	v_mfma_f32_16x16x32_bf16 v[112:115], v[140:143], v[192:195], v[112:115]
	v_mfma_f32_16x16x32_bf16 v[108:111], v[132:135], v[200:203], v[108:111]
	v_mfma_f32_16x16x32_bf16 v[100:103], v[140:143], v[200:203], v[100:103]
	v_mfma_f32_16x16x32_bf16 v[92:95], v[132:135], v[208:211], v[92:95]
	v_mfma_f32_16x16x32_bf16 v[76:79], v[140:143], v[208:211], v[76:79]
	s_setprio 0
	s_setprio 1
	v_mfma_f32_16x16x32_bf16 v[104:107], v[158:161], v[180:183], 0
	v_mfma_f32_16x16x32_bf16 v[96:99], v[172:175], v[180:183], 0
	v_mfma_f32_16x16x32_bf16 v[88:91], v[158:161], v[188:191], 0
	v_mfma_f32_16x16x32_bf16 v[84:87], v[172:175], v[188:191], 0
	v_mfma_f32_16x16x32_bf16 v[80:83], v[158:161], v[196:199], 0
	v_mfma_f32_16x16x32_bf16 v[72:75], v[172:175], v[196:199], 0
	v_mfma_f32_16x16x32_bf16 v[68:71], v[158:161], v[204:207], 0
	v_mfma_f32_16x16x32_bf16 v[64:67], v[172:175], v[204:207], 0
	v_mfma_f32_16x16x32_bf16 v[104:107], v[168:171], v[184:187], v[104:107]
	v_mfma_f32_16x16x32_bf16 v[96:99], v[176:179], v[184:187], v[96:99]
	v_mfma_f32_16x16x32_bf16 v[88:91], v[168:171], v[192:195], v[88:91]
	v_mfma_f32_16x16x32_bf16 v[84:87], v[176:179], v[192:195], v[84:87]
	v_mfma_f32_16x16x32_bf16 v[80:83], v[168:171], v[200:203], v[80:83]
	v_mfma_f32_16x16x32_bf16 v[72:75], v[176:179], v[200:203], v[72:75]
	v_mfma_f32_16x16x32_bf16 v[68:71], v[168:171], v[208:211], v[68:71]
	v_mfma_f32_16x16x32_bf16 v[64:67], v[176:179], v[208:211], v[64:67]
	s_setprio 0
	s_barrier
	s_add_i32 s66, s55, s44
	v_lshl_add_u64 v[212:213], s[36:37], 0, v[144:145]
	s_mov_b32 m0, s66
	ds_read_b128 v[180:183], v166 offset:16384
	ds_read_b128 v[184:187], v166 offset:17408
	ds_read_b128 v[188:191], v166 offset:18432
	ds_read_b128 v[192:195], v166 offset:19456
	ds_read_b128 v[196:199], v166 offset:20480
	ds_read_b128 v[200:203], v166 offset:21504
	ds_read_b128 v[204:207], v166 offset:22528
	ds_read_b128 v[208:211], v166 offset:23552
	global_load_lds_dwordx4 v[212:213], off
	s_add_i32 m0, s66, 0x2000
	s_add_u32 s66, s36, 0x40000
	v_lshl_add_u64 v[214:215], s[36:37], 0, v[146:147]
	s_addc_u32 s67, s37, 0
	s_add_i32 s68, s56, s44
	global_load_lds_dwordx4 v[214:215], off
	v_lshl_add_u64 v[216:217], s[66:67], 0, v[144:145]
	s_mov_b32 m0, s68
	v_lshl_add_u64 v[218:219], s[38:39], 0, v[146:147]
	global_load_lds_dwordx4 v[216:217], off
	v_lshl_add_u64 v[216:217], s[66:67], 0, v[146:147]
	s_add_i32 m0, s68, 0x2000
	s_nop 0
	global_load_lds_dwordx4 v[216:217], off
	v_lshl_add_u64 v[216:217], s[38:39], 0, v[144:145]
	s_mov_b32 m0, s45
	s_nop 0
	global_load_lds_dwordx4 v[216:217], off
	s_mov_b32 m0, s46
	s_nop 0
	global_load_lds_dwordx4 v[218:219], off
	s_waitcnt vmcnt(8)
	s_waitcnt lgkmcnt(0)
	s_barrier
; #define PG8_STAGE(bufoff, gbase, voff) do { _Pragma("unroll") for (int _i = 0; _i < 2; ++_i) \
;         __builtin_amdgcn_global_load_lds((const unsigned*)((const char*)(gbase) + (voff)[_i]), (PG8_LAS unsigned*)(lds + (bufoff) + ldsw + _i * 8192), 16, 0, 0); } while (0)
; #define PG8_LDA(dst, b, h) do { _Pragma("unroll") for (int m = 0; m < 4; ++m) _Pragma("unroll") for (int k = 0; k < 2; ++k) dst[m][k] = *(const PG8_LAS bf16x8*)(lds + PG8_SA(b, h) + aoff + m * 2048 + k * 1024); } while (0)
; #define PG8_LDB(dst, b, h) do { _Pragma("unroll") for (int n = 0; n < 2; ++n) _Pragma("unroll") for (int k = 0; k < 2; ++k) dst[n][k] = *(const PG8_LAS bf16x8*)(lds + PG8_SB(b, h) + boff + n * 2048 + k * 1024); } while (0)
; #define PG8_MMA(ai, bj, At, Bt) do { __builtin_amdgcn_s_setprio(1); _Pragma("unroll") for (int m = 0; m < 4; ++m) _Pragma("unroll") for (int n = 0; n < 2; ++n) _Pragma("unroll") for (int k = 0; k < 2; ++k) \
;         acc[ai][bj][m][n] = __builtin_amdgcn_mfma_f32_16x16x32_bf16(Bt[n][k], At[m][k], acc[ai][bj][m][n], 0, 0, 0); __builtin_amdgcn_s_setprio(0); } while (0)
; #define PG8_WAIT_V(n) asm volatile("s_waitcnt vmcnt(" #n ")" ::: "memory")
; #define PG8_WAIT_L(n) asm volatile("s_waitcnt lgkmcnt(" #n ")" ::: "memory")
; #define PG8_BAR __builtin_amdgcn_s_barrier()
; #define PG8_SCHED __builtin_amdgcn_sched_barrier(0)
; template <class Epi, class Sched, bool ALIGN_EPI = false, bool SP2 = false>
; __device__ __forceinline__ void gemm_phase(PG8_LAS unsigned char* lds, const Gemm g, const Sched& S, const Epi& E) {
;     ...
;             PG8_WAIT_V(8); PG8_WAIT_L(0); PG8_BAR; PG8_MMA(1, 0, At, B0); PG8_MMA(1, 1, At, B1); PG8_BAR; PG8_SCHED;
;             PG8_LDB(B0, 1, 0); PG8_LDB(B1, 1, 1); PG8_SCHED; PG8_LDA(At, 1, 0); PG8_STAGE(PG8_SA(0, 1), a2 + hstep, voffA);
;             PG8_WAIT_V(8); PG8_WAIT_L(0); PG8_BAR; PG8_MMA(0, 0, At, B0); PG8_MMA(0, 1, At, B1); PG8_BAR; PG8_SCHED;
	s_setprio 1
	s_waitcnt lgkmcnt(0)
	v_mfma_f32_16x16x32_bf16 v[60:63], v[128:131], v[180:183], 0
	v_mfma_f32_16x16x32_bf16 v[56:59], v[136:139], v[180:183], 0
	v_mfma_f32_16x16x32_bf16 v[52:55], v[128:131], v[188:191], 0
	v_mfma_f32_16x16x32_bf16 v[48:51], v[136:139], v[188:191], 0
	v_mfma_f32_16x16x32_bf16 v[32:35], v[128:131], v[196:199], 0
	v_mfma_f32_16x16x32_bf16 v[24:27], v[136:139], v[196:199], 0
	v_mfma_f32_16x16x32_bf16 v[20:23], v[128:131], v[204:207], 0
	v_mfma_f32_16x16x32_bf16 v[8:11], v[136:139], v[204:207], 0
	v_mfma_f32_16x16x32_bf16 v[60:63], v[132:135], v[184:187], v[60:63]
	v_mfma_f32_16x16x32_bf16 v[56:59], v[140:143], v[184:187], v[56:59]
	v_mfma_f32_16x16x32_bf16 v[52:55], v[132:135], v[192:195], v[52:55]
	v_mfma_f32_16x16x32_bf16 v[48:51], v[140:143], v[192:195], v[48:51]
	v_mfma_f32_16x16x32_bf16 v[32:35], v[132:135], v[200:203], v[32:35]
	v_mfma_f32_16x16x32_bf16 v[24:27], v[140:143], v[200:203], v[24:27]
	v_mfma_f32_16x16x32_bf16 v[20:23], v[132:135], v[208:211], v[20:23]
	v_mfma_f32_16x16x32_bf16 v[8:11], v[140:143], v[208:211], v[8:11]
	s_setprio 0
	s_setprio 1
	v_mfma_f32_16x16x32_bf16 v[44:47], v[158:161], v[180:183], 0
	v_mfma_f32_16x16x32_bf16 v[40:43], v[172:175], v[180:183], 0
	v_mfma_f32_16x16x32_bf16 v[36:39], v[158:161], v[188:191], 0
	v_mfma_f32_16x16x32_bf16 v[28:31], v[172:175], v[188:191], 0
	v_mfma_f32_16x16x32_bf16 v[16:19], v[158:161], v[196:199], 0
	v_mfma_f32_16x16x32_bf16 v[12:15], v[172:175], v[196:199], 0
	v_mfma_f32_16x16x32_bf16 v[4:7], v[158:161], v[204:207], 0
	v_mfma_f32_16x16x32_bf16 v[0:3], v[172:175], v[204:207], 0
	v_mfma_f32_16x16x32_bf16 v[44:47], v[168:171], v[184:187], v[44:47]
	v_mfma_f32_16x16x32_bf16 v[40:43], v[176:179], v[184:187], v[40:43]
	v_mfma_f32_16x16x32_bf16 v[36:39], v[168:171], v[192:195], v[36:39]
	v_mfma_f32_16x16x32_bf16 v[28:31], v[176:179], v[192:195], v[28:31]
	v_mfma_f32_16x16x32_bf16 v[16:19], v[168:171], v[200:203], v[16:19]
	v_mfma_f32_16x16x32_bf16 v[12:15], v[176:179], v[200:203], v[12:15]
	v_mfma_f32_16x16x32_bf16 v[4:7], v[168:171], v[208:211], v[4:7]
	v_mfma_f32_16x16x32_bf16 v[0:3], v[176:179], v[208:211], v[0:3]
	s_setprio 0
	s_barrier
	s_add_i32 s66, 0, 0x18000
	s_add_i32 s67, 0, 0x1c000
	v_add_u32_e32 v140, s66, v162
	v_add_u32_e32 v167, s67, v162
	ds_read_b128 v[128:131], v140
	ds_read_b128 v[132:135], v140 offset:1024
	ds_read_b128 v[136:139], v140 offset:2048
	ds_read_b128 v[140:143], v140 offset:3072
	ds_read_b128 v[158:161], v167
	ds_read_b128 v[168:171], v167 offset:1024
	ds_read_b128 v[172:175], v167 offset:2048
	ds_read_b128 v[176:179], v167 offset:3072
	s_add_u32 s38, s38, 0x40000
	s_addc_u32 s39, s39, 0
	s_mov_b32 m0, s47
	v_lshl_add_u64 v[220:221], s[38:39], 0, v[144:145]
	ds_read_b128 v[180:183], v166 offset:32768
	ds_read_b128 v[184:187], v166 offset:33792
	ds_read_b128 v[188:191], v166 offset:34816
	ds_read_b128 v[192:195], v166 offset:35840
	ds_read_b128 v[196:199], v166 offset:36864
	ds_read_b128 v[200:203], v166 offset:37888
	ds_read_b128 v[204:207], v166 offset:38912
	ds_read_b128 v[208:211], v166 offset:39936
	global_load_lds_dwordx4 v[220:221], off
	v_lshl_add_u64 v[220:221], s[38:39], 0, v[146:147]
	s_mov_b32 m0, s48
	s_nop 0
	global_load_lds_dwordx4 v[220:221], off
	s_waitcnt vmcnt(8)
	s_waitcnt lgkmcnt(0)
	s_barrier
	s_setprio 1
	s_waitcnt lgkmcnt(0)
	v_mfma_f32_16x16x32_bf16 v[124:127], v[128:131], v[180:183], v[124:127]
	v_mfma_f32_16x16x32_bf16 v[120:123], v[136:139], v[180:183], v[120:123]
	v_mfma_f32_16x16x32_bf16 v[116:119], v[128:131], v[188:191], v[116:119]
	v_mfma_f32_16x16x32_bf16 v[112:115], v[136:139], v[188:191], v[112:115]
	v_mfma_f32_16x16x32_bf16 v[108:111], v[128:131], v[196:199], v[108:111]
	v_mfma_f32_16x16x32_bf16 v[100:103], v[136:139], v[196:199], v[100:103]
	v_mfma_f32_16x16x32_bf16 v[92:95], v[128:131], v[204:207], v[92:95]
	v_mfma_f32_16x16x32_bf16 v[76:79], v[136:139], v[204:207], v[76:79]
	v_mfma_f32_16x16x32_bf16 v[124:127], v[132:135], v[184:187], v[124:127]
	v_mfma_f32_16x16x32_bf16 v[120:123], v[140:143], v[184:187], v[120:123]
	v_mfma_f32_16x16x32_bf16 v[116:119], v[132:135], v[192:195], v[116:119]
	v_mfma_f32_16x16x32_bf16 v[112:115], v[140:143], v[192:195], v[112:115]
	v_mfma_f32_16x16x32_bf16 v[108:111], v[132:135], v[200:203], v[108:111]
	v_mfma_f32_16x16x32_bf16 v[100:103], v[140:143], v[200:203], v[100:103]
	v_mfma_f32_16x16x32_bf16 v[92:95], v[132:135], v[208:211], v[92:95]
	v_mfma_f32_16x16x32_bf16 v[76:79], v[140:143], v[208:211], v[76:79]
	s_setprio 0
	s_setprio 1
	v_mfma_f32_16x16x32_bf16 v[104:107], v[158:161], v[180:183], v[104:107]
	v_mfma_f32_16x16x32_bf16 v[96:99], v[172:175], v[180:183], v[96:99]
	v_mfma_f32_16x16x32_bf16 v[88:91], v[158:161], v[188:191], v[88:91]
	v_mfma_f32_16x16x32_bf16 v[84:87], v[172:175], v[188:191], v[84:87]
	v_mfma_f32_16x16x32_bf16 v[80:83], v[158:161], v[196:199], v[80:83]
	v_mfma_f32_16x16x32_bf16 v[72:75], v[172:175], v[196:199], v[72:75]
	v_mfma_f32_16x16x32_bf16 v[68:71], v[158:161], v[204:207], v[68:71]
	v_mfma_f32_16x16x32_bf16 v[64:67], v[172:175], v[204:207], v[64:67]
	v_mfma_f32_16x16x32_bf16 v[104:107], v[168:171], v[184:187], v[104:107]
	v_mfma_f32_16x16x32_bf16 v[96:99], v[176:179], v[184:187], v[96:99]
	v_mfma_f32_16x16x32_bf16 v[88:91], v[168:171], v[192:195], v[88:91]
	v_mfma_f32_16x16x32_bf16 v[84:87], v[176:179], v[192:195], v[84:87]
	v_mfma_f32_16x16x32_bf16 v[80:83], v[168:171], v[200:203], v[80:83]
	v_mfma_f32_16x16x32_bf16 v[72:75], v[176:179], v[200:203], v[72:75]
	v_mfma_f32_16x16x32_bf16 v[68:71], v[168:171], v[208:211], v[68:71]
	v_mfma_f32_16x16x32_bf16 v[64:67], v[176:179], v[208:211], v[64:67]
	s_setprio 0
	s_barrier
; #define PG8_STAGE(bufoff, gbase, voff) do { _Pragma("unroll") for (int _i = 0; _i < 2; ++_i) \
;         __builtin_amdgcn_global_load_lds((const unsigned*)((const char*)(gbase) + (voff)[_i]), (PG8_LAS unsigned*)(lds + (bufoff) + ldsw + _i * 8192), 16, 0, 0); } while (0)
; #define PG8_LDA(dst, b, h) do { _Pragma("unroll") for (int m = 0; m < 4; ++m) _Pragma("unroll") for (int k = 0; k < 2; ++k) dst[m][k] = *(const PG8_LAS bf16x8*)(lds + PG8_SA(b, h) + aoff + m * 2048 + k * 1024); } while (0)
; #define PG8_MMA(ai, bj, At, Bt) do { __builtin_amdgcn_s_setprio(1); _Pragma("unroll") for (int m = 0; m < 4; ++m) _Pragma("unroll") for (int n = 0; n < 2; ++n) _Pragma("unroll") for (int k = 0; k < 2; ++k) \
;         acc[ai][bj][m][n] = __builtin_amdgcn_mfma_f32_16x16x32_bf16(Bt[n][k], At[m][k], acc[ai][bj][m][n], 0, 0, 0); __builtin_amdgcn_s_setprio(0); } while (0)
; #define PG8_WAIT_V(n) asm volatile("s_waitcnt vmcnt(" #n ")" ::: "memory")
; #define PG8_WAIT_L(n) asm volatile("s_waitcnt lgkmcnt(" #n ")" ::: "memory")
; #define PG8_BAR __builtin_amdgcn_s_barrier()
; #define PG8_SCHED __builtin_amdgcn_sched_barrier(0)
; template <class Epi, class Sched, bool ALIGN_EPI = false, bool SP2 = false>
; __device__ __forceinline__ void gemm_phase(PG8_LAS unsigned char* lds, const Gemm g, const Sched& S, const Epi& E) {
;     ...
;             PG8_LDA(At, 1, 1); PG8_STAGE(PG8_SB(1, 0), b3, voffB); PG8_STAGE(PG8_SB(1, 1), b3 + hstep, voffB); PG8_STAGE(PG8_SA(1, 0), a3, voffA);
;             PG8_WAIT_V(8); PG8_WAIT_L(0); PG8_BAR; PG8_MMA(1, 0, At, B0); PG8_MMA(1, 1, At, B1); PG8_BAR; PG8_SCHED;
	s_add_i32 s38, s66, s44
	v_lshl_add_u64 v[212:213], v[212:213], 0, s[10:11]
	s_mov_b32 m0, s38
	ds_read_b128 v[180:183], v166 offset:49152
	ds_read_b128 v[184:187], v166 offset:50176
	ds_read_b128 v[188:191], v166 offset:51200
	ds_read_b128 v[192:195], v166 offset:52224
	ds_read_b128 v[196:199], v166 offset:53248
	ds_read_b128 v[200:203], v166 offset:54272
	ds_read_b128 v[204:207], v166 offset:55296
	ds_read_b128 v[208:211], v166 offset:56320
	global_load_lds_dwordx4 v[212:213], off
	s_add_i32 m0, s38, 0x2000
	s_add_u32 s36, s36, 0x40080
	v_lshl_add_u64 v[212:213], v[214:215], 0, s[10:11]
	s_addc_u32 s37, s37, 0
	s_add_i32 s38, s67, s44
	global_load_lds_dwordx4 v[212:213], off
	v_lshl_add_u64 v[212:213], s[36:37], 0, v[144:145]
	s_mov_b32 m0, s38
	s_nop 0
	global_load_lds_dwordx4 v[212:213], off
	v_lshl_add_u64 v[212:213], s[36:37], 0, v[146:147]
	s_add_i32 m0, s38, 0x2000
	s_nop 0
	global_load_lds_dwordx4 v[212:213], off
	v_lshl_add_u64 v[212:213], v[216:217], 0, s[10:11]
	s_mov_b32 m0, s52
	s_nop 0
	global_load_lds_dwordx4 v[212:213], off
	v_lshl_add_u64 v[212:213], v[218:219], 0, s[10:11]
	s_mov_b32 m0, s53
	s_nop 0
	global_load_lds_dwordx4 v[212:213], off
	s_waitcnt vmcnt(8)
	s_waitcnt lgkmcnt(0)
	s_barrier
	s_setprio 1
	s_waitcnt lgkmcnt(0)
	v_mfma_f32_16x16x32_bf16 v[60:63], v[128:131], v[180:183], v[60:63]
	v_mfma_f32_16x16x32_bf16 v[56:59], v[136:139], v[180:183], v[56:59]
	v_mfma_f32_16x16x32_bf16 v[52:55], v[128:131], v[188:191], v[52:55]
	v_mfma_f32_16x16x32_bf16 v[48:51], v[136:139], v[188:191], v[48:51]
	v_mfma_f32_16x16x32_bf16 v[32:35], v[128:131], v[196:199], v[32:35]
	v_mfma_f32_16x16x32_bf16 v[24:27], v[136:139], v[196:199], v[24:27]
	v_mfma_f32_16x16x32_bf16 v[20:23], v[128:131], v[204:207], v[20:23]
	v_mfma_f32_16x16x32_bf16 v[8:11], v[136:139], v[204:207], v[8:11]
	v_mfma_f32_16x16x32_bf16 v[60:63], v[132:135], v[184:187], v[60:63]
	v_mfma_f32_16x16x32_bf16 v[56:59], v[140:143], v[184:187], v[56:59]
	v_mfma_f32_16x16x32_bf16 v[52:55], v[132:135], v[192:195], v[52:55]
	v_mfma_f32_16x16x32_bf16 v[48:51], v[140:143], v[192:195], v[48:51]
	v_mfma_f32_16x16x32_bf16 v[32:35], v[132:135], v[200:203], v[32:35]
	v_mfma_f32_16x16x32_bf16 v[24:27], v[140:143], v[200:203], v[24:27]
	v_mfma_f32_16x16x32_bf16 v[20:23], v[132:135], v[208:211], v[20:23]
	v_mfma_f32_16x16x32_bf16 v[8:11], v[140:143], v[208:211], v[8:11]
	s_setprio 0
	s_setprio 1
	v_mfma_f32_16x16x32_bf16 v[44:47], v[158:161], v[180:183], v[44:47]
	v_mfma_f32_16x16x32_bf16 v[40:43], v[172:175], v[180:183], v[40:43]
	v_mfma_f32_16x16x32_bf16 v[36:39], v[158:161], v[188:191], v[36:39]
	v_mfma_f32_16x16x32_bf16 v[28:31], v[172:175], v[188:191], v[28:31]
	v_mfma_f32_16x16x32_bf16 v[16:19], v[158:161], v[196:199], v[16:19]
	v_mfma_f32_16x16x32_bf16 v[12:15], v[172:175], v[196:199], v[12:15]
	v_mfma_f32_16x16x32_bf16 v[4:7], v[158:161], v[204:207], v[4:7]
	v_mfma_f32_16x16x32_bf16 v[0:3], v[172:175], v[204:207], v[0:3]
	v_mfma_f32_16x16x32_bf16 v[44:47], v[168:171], v[184:187], v[44:47]
	v_mfma_f32_16x16x32_bf16 v[40:43], v[176:179], v[184:187], v[40:43]
	v_mfma_f32_16x16x32_bf16 v[36:39], v[168:171], v[192:195], v[36:39]
	v_mfma_f32_16x16x32_bf16 v[28:31], v[176:179], v[192:195], v[28:31]
	v_mfma_f32_16x16x32_bf16 v[16:19], v[168:171], v[200:203], v[16:19]
	v_mfma_f32_16x16x32_bf16 v[12:15], v[176:179], v[200:203], v[12:15]
	v_mfma_f32_16x16x32_bf16 v[4:7], v[168:171], v[208:211], v[4:7]
	v_mfma_f32_16x16x32_bf16 v[0:3], v[176:179], v[208:211], v[0:3]
	s_setprio 0
	s_barrier
	s_add_i32 s65, s65, 2
	s_add_u32 s34, s34, 0x100
	s_addc_u32 s35, s35, 0
	s_add_u32 s63, s63, 0x100
	s_addc_u32 s64, s64, 0
	s_cmp_gt_u32 s65, 13
